# overlapped final norm paced with s_sleep 40 per 4-row chunk so it spreads over P9 round 2 instead of competing for HBM early
# speedup vs baseline: 1.0017x; 1.0017x over previous
.Lp10a_loop:
	s_sleep 40
	s_add_u32 s8, s12, 0x1000
	s_addc_u32 s9, s13, 0
	global_load_dwordx2 v[20:21], v1, s[12:13] nt
	global_load_dwordx2 v[22:23], v1, s[12:13] offset:512 nt
	global_load_dwordx2 v[24:25], v1, s[12:13] offset:1024 nt
	global_load_dwordx2 v[26:27], v1, s[12:13] offset:1536 nt
	global_load_dwordx2 v[28:29], v1, s[12:13] offset:2048 nt
	global_load_dwordx2 v[30:31], v1, s[12:13] offset:2560 nt
	global_load_dwordx2 v[32:33], v1, s[12:13] offset:3072 nt
	global_load_dwordx2 v[34:35], v1, s[12:13] offset:3584 nt
	global_load_dwordx2 v[36:37], v1, s[8:9] nt
	global_load_dwordx2 v[38:39], v1, s[8:9] offset:512 nt
	global_load_dwordx2 v[40:41], v1, s[8:9] offset:1024 nt
	global_load_dwordx2 v[42:43], v1, s[8:9] offset:1536 nt
	global_load_dwordx2 v[44:45], v1, s[8:9] offset:2048 nt
	global_load_dwordx2 v[46:47], v1, s[8:9] offset:2560 nt
	global_load_dwordx2 v[48:49], v1, s[8:9] offset:3072 nt
	global_load_dwordx2 v[50:51], v1, s[8:9] offset:3584 nt
	s_waitcnt vmcnt(0)
	v_lshlrev_b32_e32 v52, 16, v20
	v_and_b32_e32 v53, 0xffff0000, v20
	v_lshlrev_b32_e32 v54, 16, v21
	v_and_b32_e32 v55, 0xffff0000, v21
	v_lshlrev_b32_e32 v56, 16, v22
	v_and_b32_e32 v57, 0xffff0000, v22
	v_lshlrev_b32_e32 v58, 16, v23
	v_and_b32_e32 v59, 0xffff0000, v23
	v_lshlrev_b32_e32 v60, 16, v24
	v_and_b32_e32 v61, 0xffff0000, v24
	v_lshlrev_b32_e32 v62, 16, v25
	v_and_b32_e32 v63, 0xffff0000, v25
	v_lshlrev_b32_e32 v64, 16, v26
	v_and_b32_e32 v65, 0xffff0000, v26
	v_lshlrev_b32_e32 v66, 16, v27
	v_and_b32_e32 v67, 0xffff0000, v27
	v_lshlrev_b32_e32 v68, 16, v28
	v_and_b32_e32 v69, 0xffff0000, v28
	v_lshlrev_b32_e32 v70, 16, v29
	v_and_b32_e32 v71, 0xffff0000, v29
	v_lshlrev_b32_e32 v72, 16, v30
	v_and_b32_e32 v73, 0xffff0000, v30
	v_lshlrev_b32_e32 v74, 16, v31
	v_and_b32_e32 v75, 0xffff0000, v31
	v_lshlrev_b32_e32 v76, 16, v32
	v_and_b32_e32 v77, 0xffff0000, v32
	v_lshlrev_b32_e32 v78, 16, v33
	v_and_b32_e32 v79, 0xffff0000, v33
	v_lshlrev_b32_e32 v80, 16, v34
	v_and_b32_e32 v81, 0xffff0000, v34
	v_lshlrev_b32_e32 v82, 16, v35
	v_and_b32_e32 v83, 0xffff0000, v35
	v_lshlrev_b32_e32 v84, 16, v36
	v_and_b32_e32 v85, 0xffff0000, v36
	v_lshlrev_b32_e32 v86, 16, v37
	v_and_b32_e32 v87, 0xffff0000, v37
	v_lshlrev_b32_e32 v88, 16, v38
	v_and_b32_e32 v89, 0xffff0000, v38
	v_lshlrev_b32_e32 v90, 16, v39
	v_and_b32_e32 v91, 0xffff0000, v39
	v_lshlrev_b32_e32 v92, 16, v40
	v_and_b32_e32 v93, 0xffff0000, v40
	v_lshlrev_b32_e32 v94, 16, v41
	v_and_b32_e32 v95, 0xffff0000, v41
	v_lshlrev_b32_e32 v96, 16, v42
	v_and_b32_e32 v97, 0xffff0000, v42
	v_lshlrev_b32_e32 v98, 16, v43
	v_and_b32_e32 v99, 0xffff0000, v43
	v_lshlrev_b32_e32 v100, 16, v44
	v_and_b32_e32 v101, 0xffff0000, v44
	v_lshlrev_b32_e32 v102, 16, v45
	v_and_b32_e32 v103, 0xffff0000, v45
	v_lshlrev_b32_e32 v104, 16, v46
	v_and_b32_e32 v105, 0xffff0000, v46
	v_lshlrev_b32_e32 v106, 16, v47
	v_and_b32_e32 v107, 0xffff0000, v47
	v_lshlrev_b32_e32 v108, 16, v48
	v_and_b32_e32 v109, 0xffff0000, v48
	v_lshlrev_b32_e32 v110, 16, v49
	v_and_b32_e32 v111, 0xffff0000, v49
	v_lshlrev_b32_e32 v112, 16, v50
	v_and_b32_e32 v113, 0xffff0000, v50
	v_lshlrev_b32_e32 v114, 16, v51
	v_and_b32_e32 v115, 0xffff0000, v51
	v_mul_f32_e32 v116, v52, v52
	v_mul_f32_e32 v117, v68, v68
	v_mul_f32_e32 v118, v84, v84
	v_mul_f32_e32 v119, v100, v100
	v_fmac_f32_e32 v116, v53, v53
	v_fmac_f32_e32 v117, v69, v69
	v_fmac_f32_e32 v118, v85, v85
	v_fmac_f32_e32 v119, v101, v101
	v_fmac_f32_e32 v116, v54, v54
	v_fmac_f32_e32 v117, v70, v70
	v_fmac_f32_e32 v118, v86, v86
	v_fmac_f32_e32 v119, v102, v102
	v_fmac_f32_e32 v116, v55, v55
	v_fmac_f32_e32 v117, v71, v71
	v_fmac_f32_e32 v118, v87, v87
	v_fmac_f32_e32 v119, v103, v103
	v_fmac_f32_e32 v116, v56, v56
	v_fmac_f32_e32 v117, v72, v72
	v_fmac_f32_e32 v118, v88, v88
	v_fmac_f32_e32 v119, v104, v104
	v_fmac_f32_e32 v116, v57, v57
	v_fmac_f32_e32 v117, v73, v73
	v_fmac_f32_e32 v118, v89, v89
	v_fmac_f32_e32 v119, v105, v105
	v_fmac_f32_e32 v116, v58, v58
	v_fmac_f32_e32 v117, v74, v74
	v_fmac_f32_e32 v118, v90, v90
	v_fmac_f32_e32 v119, v106, v106
	v_fmac_f32_e32 v116, v59, v59
	v_fmac_f32_e32 v117, v75, v75
	v_fmac_f32_e32 v118, v91, v91
	v_fmac_f32_e32 v119, v107, v107
	v_fmac_f32_e32 v116, v60, v60
	v_fmac_f32_e32 v117, v76, v76
	v_fmac_f32_e32 v118, v92, v92
	v_fmac_f32_e32 v119, v108, v108
	v_fmac_f32_e32 v116, v61, v61
	v_fmac_f32_e32 v117, v77, v77
	v_fmac_f32_e32 v118, v93, v93
	v_fmac_f32_e32 v119, v109, v109
	v_fmac_f32_e32 v116, v62, v62
	v_fmac_f32_e32 v117, v78, v78
	v_fmac_f32_e32 v118, v94, v94
	v_fmac_f32_e32 v119, v110, v110
	v_fmac_f32_e32 v116, v63, v63
	v_fmac_f32_e32 v117, v79, v79
	v_fmac_f32_e32 v118, v95, v95
	v_fmac_f32_e32 v119, v111, v111
	v_fmac_f32_e32 v116, v64, v64
	v_fmac_f32_e32 v117, v80, v80
	v_fmac_f32_e32 v118, v96, v96
	v_fmac_f32_e32 v119, v112, v112
	v_fmac_f32_e32 v116, v65, v65
	v_fmac_f32_e32 v117, v81, v81
	v_fmac_f32_e32 v118, v97, v97
	v_fmac_f32_e32 v119, v113, v113
	v_fmac_f32_e32 v116, v66, v66
	v_fmac_f32_e32 v117, v82, v82
	v_fmac_f32_e32 v118, v98, v98
	v_fmac_f32_e32 v119, v114, v114
	v_fmac_f32_e32 v116, v67, v67
	v_fmac_f32_e32 v117, v83, v83
	v_fmac_f32_e32 v118, v99, v99
	v_fmac_f32_e32 v119, v115, v115
	v_add_f32_dpp v132, v116, v116 quad_perm:[1,0,3,2] row_mask:0xf bank_mask:0xf
	v_add_f32_dpp v133, v117, v117 quad_perm:[1,0,3,2] row_mask:0xf bank_mask:0xf
	v_add_f32_dpp v134, v118, v118 quad_perm:[1,0,3,2] row_mask:0xf bank_mask:0xf
	v_add_f32_dpp v135, v119, v119 quad_perm:[1,0,3,2] row_mask:0xf bank_mask:0xf
	v_add_f32_dpp v136, v132, v132 quad_perm:[2,3,0,1] row_mask:0xf bank_mask:0xf
	v_add_f32_dpp v137, v133, v133 quad_perm:[2,3,0,1] row_mask:0xf bank_mask:0xf
	v_add_f32_dpp v138, v134, v134 quad_perm:[2,3,0,1] row_mask:0xf bank_mask:0xf
	v_add_f32_dpp v139, v135, v135 quad_perm:[2,3,0,1] row_mask:0xf bank_mask:0xf
	v_add_f32_dpp v132, v136, v136 row_ror:4 row_mask:0xf bank_mask:0xf
	v_add_f32_dpp v133, v137, v137 row_ror:4 row_mask:0xf bank_mask:0xf
	v_add_f32_dpp v134, v138, v138 row_ror:4 row_mask:0xf bank_mask:0xf
	v_add_f32_dpp v135, v139, v139 row_ror:4 row_mask:0xf bank_mask:0xf
	v_add_f32_dpp v136, v132, v132 row_ror:8 row_mask:0xf bank_mask:0xf
	v_add_f32_dpp v137, v133, v133 row_ror:8 row_mask:0xf bank_mask:0xf
	v_add_f32_dpp v138, v134, v134 row_ror:8 row_mask:0xf bank_mask:0xf
	v_add_f32_dpp v139, v135, v135 row_ror:8 row_mask:0xf bank_mask:0xf
	s_nop 1
	v_readlane_b32 s16, v136, 0
	v_readlane_b32 s17, v136, 16
	v_readlane_b32 s18, v136, 32
	v_readlane_b32 s19, v136, 48
	v_readlane_b32 s20, v137, 0
	v_readlane_b32 s21, v137, 16
	v_readlane_b32 s22, v137, 32
	v_readlane_b32 s23, v137, 48
	v_readlane_b32 s24, v138, 0
	v_readlane_b32 s25, v138, 16
	v_readlane_b32 s26, v138, 32
	v_readlane_b32 s27, v138, 48
	v_readlane_b32 s28, v139, 0
	v_readlane_b32 s29, v139, 16
	v_readlane_b32 s30, v139, 32
	v_readlane_b32 s31, v139, 48
	s_nop 1
	v_mov_b32_e32 v132, s16
	v_mov_b32_e32 v133, s20
	v_mov_b32_e32 v134, s24
	v_mov_b32_e32 v135, s28
	v_add_f32_e32 v132, s17, v132
	v_add_f32_e32 v133, s21, v133
	v_add_f32_e32 v134, s25, v134
	v_add_f32_e32 v135, s29, v135
	v_add_f32_e32 v132, s18, v132
	v_add_f32_e32 v133, s22, v133
	v_add_f32_e32 v134, s26, v134
	v_add_f32_e32 v135, s30, v135
	v_add_f32_e32 v132, s19, v132
	v_add_f32_e32 v133, s23, v133
	v_add_f32_e32 v134, s27, v134
	v_add_f32_e32 v135, s31, v135
	v_fma_f32 v140, v132, v3, v121
	v_fma_f32 v141, v133, v3, v121
	v_fma_f32 v142, v134, v3, v121
	v_fma_f32 v143, v135, v3, v121
	v_rsq_f32_e32 v124, v140
	v_rsq_f32_e32 v126, v141
	v_rsq_f32_e32 v128, v142
	v_rsq_f32_e32 v130, v143
	s_nop 0
	v_mul_f32_e32 v132, v140, v124
	v_mul_f32_e32 v133, v141, v126
	v_mul_f32_e32 v134, v142, v128
	v_mul_f32_e32 v135, v143, v130
	v_mul_f32_e32 v132, v132, v124
	v_mul_f32_e32 v133, v133, v126
	v_mul_f32_e32 v134, v134, v128
	v_mul_f32_e32 v135, v135, v130
	v_sub_f32_e32 v132, 1.0, v132
	v_sub_f32_e32 v133, 1.0, v133
	v_sub_f32_e32 v134, 1.0, v134
	v_sub_f32_e32 v135, 1.0, v135
	v_mul_f32_e32 v136, 0.5, v124
	v_mul_f32_e32 v137, 0.5, v126
	v_mul_f32_e32 v138, 0.5, v128
	v_mul_f32_e32 v139, 0.5, v130
	v_fmac_f32_e32 v124, v136, v132
	v_fmac_f32_e32 v126, v137, v133
	v_fmac_f32_e32 v128, v138, v134
	v_fmac_f32_e32 v130, v139, v135
	v_pk_mul_f32 v[52:53], v[52:53], v[124:125] op_sel_hi:[1,0]
	v_pk_mul_f32 v[54:55], v[54:55], v[124:125] op_sel_hi:[1,0]
	v_pk_mul_f32 v[56:57], v[56:57], v[124:125] op_sel_hi:[1,0]
	v_pk_mul_f32 v[58:59], v[58:59], v[124:125] op_sel_hi:[1,0]
	v_pk_mul_f32 v[60:61], v[60:61], v[124:125] op_sel_hi:[1,0]
	v_pk_mul_f32 v[62:63], v[62:63], v[124:125] op_sel_hi:[1,0]
	v_pk_mul_f32 v[64:65], v[64:65], v[124:125] op_sel_hi:[1,0]
	v_pk_mul_f32 v[66:67], v[66:67], v[124:125] op_sel_hi:[1,0]
	v_pk_mul_f32 v[52:53], v[52:53], v[4:5]
	v_pk_mul_f32 v[54:55], v[54:55], v[6:7]
	v_pk_mul_f32 v[56:57], v[56:57], v[8:9]
	v_pk_mul_f32 v[58:59], v[58:59], v[10:11]
	v_pk_mul_f32 v[60:61], v[60:61], v[12:13]
	v_pk_mul_f32 v[62:63], v[62:63], v[14:15]
	v_pk_mul_f32 v[64:65], v[64:65], v[16:17]
	v_pk_mul_f32 v[66:67], v[66:67], v[18:19]
	global_store_dwordx4 v2, v[52:55], s[14:15] nt
	global_store_dwordx4 v2, v[56:59], s[14:15] offset:1024 nt
	global_store_dwordx4 v2, v[60:63], s[14:15] offset:2048 nt
	global_store_dwordx4 v2, v[64:67], s[14:15] offset:3072 nt
	v_pk_mul_f32 v[68:69], v[68:69], v[126:127] op_sel_hi:[1,0]
	v_pk_mul_f32 v[70:71], v[70:71], v[126:127] op_sel_hi:[1,0]
	v_pk_mul_f32 v[72:73], v[72:73], v[126:127] op_sel_hi:[1,0]
	v_pk_mul_f32 v[74:75], v[74:75], v[126:127] op_sel_hi:[1,0]
	v_pk_mul_f32 v[76:77], v[76:77], v[126:127] op_sel_hi:[1,0]
	v_pk_mul_f32 v[78:79], v[78:79], v[126:127] op_sel_hi:[1,0]
	v_pk_mul_f32 v[80:81], v[80:81], v[126:127] op_sel_hi:[1,0]
	v_pk_mul_f32 v[82:83], v[82:83], v[126:127] op_sel_hi:[1,0]
	v_pk_mul_f32 v[68:69], v[68:69], v[4:5]
	v_pk_mul_f32 v[70:71], v[70:71], v[6:7]
	v_pk_mul_f32 v[72:73], v[72:73], v[8:9]
	v_pk_mul_f32 v[74:75], v[74:75], v[10:11]
	v_pk_mul_f32 v[76:77], v[76:77], v[12:13]
	v_pk_mul_f32 v[78:79], v[78:79], v[14:15]
	v_pk_mul_f32 v[80:81], v[80:81], v[16:17]
	v_pk_mul_f32 v[82:83], v[82:83], v[18:19]
	s_add_u32 s2, s14, 0x1000
	s_addc_u32 s3, s15, 0
	global_store_dwordx4 v2, v[68:71], s[2:3] nt
	global_store_dwordx4 v2, v[72:75], s[2:3] offset:1024 nt
	global_store_dwordx4 v2, v[76:79], s[2:3] offset:2048 nt
	global_store_dwordx4 v2, v[80:83], s[2:3] offset:3072 nt
	v_pk_mul_f32 v[84:85], v[84:85], v[128:129] op_sel_hi:[1,0]
	v_pk_mul_f32 v[86:87], v[86:87], v[128:129] op_sel_hi:[1,0]
	v_pk_mul_f32 v[88:89], v[88:89], v[128:129] op_sel_hi:[1,0]
	v_pk_mul_f32 v[90:91], v[90:91], v[128:129] op_sel_hi:[1,0]
	v_pk_mul_f32 v[92:93], v[92:93], v[128:129] op_sel_hi:[1,0]
	v_pk_mul_f32 v[94:95], v[94:95], v[128:129] op_sel_hi:[1,0]
	v_pk_mul_f32 v[96:97], v[96:97], v[128:129] op_sel_hi:[1,0]
	v_pk_mul_f32 v[98:99], v[98:99], v[128:129] op_sel_hi:[1,0]
	v_pk_mul_f32 v[84:85], v[84:85], v[4:5]
	v_pk_mul_f32 v[86:87], v[86:87], v[6:7]
	v_pk_mul_f32 v[88:89], v[88:89], v[8:9]
	v_pk_mul_f32 v[90:91], v[90:91], v[10:11]
	v_pk_mul_f32 v[92:93], v[92:93], v[12:13]
	v_pk_mul_f32 v[94:95], v[94:95], v[14:15]
	v_pk_mul_f32 v[96:97], v[96:97], v[16:17]
	v_pk_mul_f32 v[98:99], v[98:99], v[18:19]
	s_add_u32 s2, s14, 0x2000
	s_addc_u32 s3, s15, 0
	global_store_dwordx4 v2, v[84:87], s[2:3] nt
	global_store_dwordx4 v2, v[88:91], s[2:3] offset:1024 nt
	global_store_dwordx4 v2, v[92:95], s[2:3] offset:2048 nt
	global_store_dwordx4 v2, v[96:99], s[2:3] offset:3072 nt
	v_pk_mul_f32 v[100:101], v[100:101], v[130:131] op_sel_hi:[1,0]
	v_pk_mul_f32 v[102:103], v[102:103], v[130:131] op_sel_hi:[1,0]
	v_pk_mul_f32 v[104:105], v[104:105], v[130:131] op_sel_hi:[1,0]
	v_pk_mul_f32 v[106:107], v[106:107], v[130:131] op_sel_hi:[1,0]
	v_pk_mul_f32 v[108:109], v[108:109], v[130:131] op_sel_hi:[1,0]
	v_pk_mul_f32 v[110:111], v[110:111], v[130:131] op_sel_hi:[1,0]
	v_pk_mul_f32 v[112:113], v[112:113], v[130:131] op_sel_hi:[1,0]
	v_pk_mul_f32 v[114:115], v[114:115], v[130:131] op_sel_hi:[1,0]
	v_pk_mul_f32 v[100:101], v[100:101], v[4:5]
	v_pk_mul_f32 v[102:103], v[102:103], v[6:7]
	v_pk_mul_f32 v[104:105], v[104:105], v[8:9]
	v_pk_mul_f32 v[106:107], v[106:107], v[10:11]
	v_pk_mul_f32 v[108:109], v[108:109], v[12:13]
	v_pk_mul_f32 v[110:111], v[110:111], v[14:15]
	v_pk_mul_f32 v[112:113], v[112:113], v[16:17]
	v_pk_mul_f32 v[114:115], v[114:115], v[18:19]
	s_add_u32 s2, s14, 0x3000
	s_addc_u32 s3, s15, 0
	global_store_dwordx4 v2, v[100:103], s[2:3] nt
	global_store_dwordx4 v2, v[104:107], s[2:3] offset:1024 nt
	global_store_dwordx4 v2, v[108:111], s[2:3] offset:2048 nt
	global_store_dwordx4 v2, v[112:115], s[2:3] offset:3072 nt
	s_add_u32 s12, s12, 0x2000
	s_addc_u32 s13, s13, 0
	s_add_u32 s14, s14, 0x4000
	s_addc_u32 s15, s15, 0
	s_add_i32 s10, s10, -1
	s_cmp_lg_u32 s10, 0
	s_cbranch_scc1 .Lp10a_loop
